# adds: redundant L2 write-back (buffer_wbl2) removed at grid seams 0 and 1; P0 row-sum / mem-row stores made write-through
# baseline (speedup 1.0000x reference)
; __global__ void __launch_bounds__(512, 2) fwd_mega(Args a) {
;     ...
;         for (int m = gw; m < M; m += 2 * NGW) {
;             const int m2 = (m + NGW < M) ? m + NGW : m;
;             const f32x4* xr0 = (const f32x4*)(x + (size_t)m * D) + 2 * lane; const f32x4* xr1 = (const f32x4*)(x + (size_t)m2 * D) + 2 * lane;
;             f32x4 v0[4], v1[4]; float s0 = 0.f, s1 = 0.f;
; #pragma unroll
;             for (int j = 0; j < 2; ++j) { v0[2 * j] = xr0[128 * j]; v0[2 * j + 1] = xr0[128 * j + 1]; v1[2 * j] = xr1[128 * j]; v1[2 * j + 1] = xr1[128 * j + 1]; }
; #pragma unroll
;             for (int j = 0; j < 4; ++j) { s0 += (v0[j].x * v0[j].x + v0[j].y * v0[j].y) + (v0[j].z * v0[j].z + v0[j].w * v0[j].w); s1 += (v1[j].x * v1[j].x + v1[j].y * v1[j].y) + (v1[j].z * v1[j].z + v1[j].w * v1[j].w); }
; #pragma unroll
;             for (int o = 1; o < 64; o <<= 1) { s0 += __shfl_xor(s0, o); s1 += __shfl_xor(s1, o); }
;             if (lane == 0) { RSQX[m] = s0; RSQX[m2] = s1; }
.LBB0_60:
	s_add_i32 s3, s6, s80
	s_cmpk_lt_i32 s3, 0x4000
	s_cselect_b32 s8, s3, s6
	s_ashr_i32 s7, s6, 31
	s_lshl_b64 s[14:15], s[6:7], 12
	s_ashr_i32 s9, s8, 31
	v_lshl_add_u64 v[0:1], v[34:35], 0, s[14:15]
	s_lshl_b64 s[14:15], s[8:9], 12
	global_load_dwordx4 v[28:31], v[0:1], off
	global_load_dwordx4 v[24:27], v[0:1], off offset:16
	global_load_dwordx4 v[12:15], v[0:1], off offset:2048
	global_load_dwordx4 v[8:11], v[0:1], off offset:2064
	v_lshl_add_u64 v[0:1], v[34:35], 0, s[14:15]
	global_load_dwordx4 v[20:23], v[0:1], off
	global_load_dwordx4 v[16:19], v[0:1], off offset:16
	global_load_dwordx4 v[4:7], v[0:1], off offset:2048
	s_nop 0
	global_load_dwordx4 v[0:3], v[0:1], off offset:2064
	s_waitcnt vmcnt(7)
	v_mul_f32_e32 v43, v29, v29
	v_mul_f32_e32 v44, v31, v31
	s_waitcnt vmcnt(6)
	v_mul_f32_e32 v45, v25, v25
	v_mul_f32_e32 v46, v27, v27
	s_waitcnt vmcnt(5)
	v_mul_f32_e32 v47, v13, v13
	v_mul_f32_e32 v48, v15, v15
	v_fmac_f32_e32 v43, v28, v28
	v_fmac_f32_e32 v44, v30, v30
	s_waitcnt vmcnt(3)
	v_mul_f32_e32 v51, v21, v21
	v_mul_f32_e32 v52, v23, v23
	v_fmac_f32_e32 v45, v24, v24
	v_fmac_f32_e32 v46, v26, v26
	s_waitcnt vmcnt(2)
	v_mul_f32_e32 v53, v17, v17
	v_mul_f32_e32 v54, v19, v19
	v_fmac_f32_e32 v47, v12, v12
	v_fmac_f32_e32 v48, v14, v14
	s_waitcnt vmcnt(1)
	v_mul_f32_e32 v55, v5, v5
	v_mul_f32_e32 v56, v7, v7
	v_add_f32_e32 v43, v43, v44
	v_fmac_f32_e32 v51, v20, v20
	v_fmac_f32_e32 v52, v22, v22
	v_add_f32_e32 v44, v45, v46
	v_fmac_f32_e32 v53, v16, v16
	v_fmac_f32_e32 v54, v18, v18
	v_mul_f32_e32 v49, v9, v9
	v_mul_f32_e32 v50, v11, v11
	s_waitcnt vmcnt(0)
	v_mul_f32_e32 v57, v1, v1
	v_mul_f32_e32 v58, v3, v3
	v_add_f32_e32 v45, v47, v48
	v_fmac_f32_e32 v55, v4, v4
	v_fmac_f32_e32 v56, v6, v6
	v_add_f32_e32 v47, v51, v52
	v_add_f32_e32 v43, v43, v44
	v_add_f32_e32 v44, v53, v54
	v_fmac_f32_e32 v49, v8, v8
	v_fmac_f32_e32 v50, v10, v10
	v_fmac_f32_e32 v57, v0, v0
	v_fmac_f32_e32 v58, v2, v2
	v_add_f32_e32 v48, v55, v56
	v_add_f32_e32 v44, v47, v44
	v_add_f32_e32 v46, v49, v50
	v_add_f32_e32 v49, v57, v58
	v_add_f32_e32 v43, v43, v45
	v_add_f32_e32 v44, v44, v48
	v_add_f32_e32 v43, v43, v46
	v_add_f32_e32 v44, v44, v49
	ds_bpermute_b32 v45, v32, v43
	ds_bpermute_b32 v46, v32, v44
	s_waitcnt lgkmcnt(1)
	v_add_f32_e32 v43, v43, v45
	s_waitcnt lgkmcnt(0)
	v_add_f32_e32 v44, v44, v46
	ds_bpermute_b32 v45, v38, v43
	ds_bpermute_b32 v46, v38, v44
	s_waitcnt lgkmcnt(1)
	v_add_f32_e32 v43, v43, v45
	s_waitcnt lgkmcnt(0)
	v_add_f32_e32 v44, v44, v46
	ds_bpermute_b32 v45, v39, v43
	ds_bpermute_b32 v46, v39, v44
	s_waitcnt lgkmcnt(1)
	v_add_f32_e32 v43, v43, v45
	s_waitcnt lgkmcnt(0)
	v_add_f32_e32 v44, v44, v46
	ds_bpermute_b32 v45, v40, v43
	ds_bpermute_b32 v46, v40, v44
	s_waitcnt lgkmcnt(1)
	v_add_f32_e32 v43, v43, v45
	s_waitcnt lgkmcnt(0)
	v_add_f32_e32 v44, v44, v46
	ds_bpermute_b32 v45, v41, v43
	ds_bpermute_b32 v46, v41, v44
	s_waitcnt lgkmcnt(1)
	v_add_f32_e32 v43, v43, v45
	s_waitcnt lgkmcnt(0)
	v_add_f32_e32 v44, v44, v46
	ds_bpermute_b32 v45, v42, v43
	ds_bpermute_b32 v46, v42, v44
	s_and_saveexec_b64 s[14:15], s[0:1]
	s_cbranch_execz .LBB0_62
	s_lshl_b64 s[16:17], s[8:9], 2
	s_add_u32 s16, s28, s16
	s_addc_u32 s17, s29, s17
	s_lshl_b64 s[26:27], s[6:7], 2
	s_add_u32 s26, s28, s26
	s_waitcnt lgkmcnt(1)
	v_add_f32_e32 v43, v43, v45
	s_addc_u32 s27, s29, s27
	s_waitcnt lgkmcnt(0)
	v_add_f32_e32 v44, v44, v46
	global_store_dword v33, v43, s[26:27] sc1
	global_store_dword v33, v44, s[16:17] sc1

; __device__ __forceinline__ unsigned pk2(float lo, float hi) { return pg8::cvt_pk_bf16(lo, hi); }
; __device__ __forceinline__ void rms_row_to_bf16(const float* xrow, const float* w, bf16* orow, int lane) {
;     const f32x4* xr = (const f32x4*)xrow + lane; const f32x4* wr = (const f32x4*)w + lane;
;     f32x4 v[4]; float s = 0.f;
; #pragma unroll
;     for (int j = 0; j < 4; ++j) { v[j] = xr[64 * j]; s += (v[j].x * v[j].x + v[j].y * v[j].y) + (v[j].z * v[j].z + v[j].w * v[j].w); }
;     const float rstd = rsqrtf(wave_sum(s) * (1.f / D) + EPS);
;     u32x2* o8 = (u32x2*)orow + lane;
; #pragma unroll
;     for (int j = 0; j < 4; ++j) { const f32x4 ww = wr[64 * j]; u32x2 o; o.x = pk2(v[j].x * rstd * ww.x, v[j].y * rstd * ww.y); o.y = pk2(v[j].z * rstd * ww.z, v[j].w * rstd * ww.w); o8[64 * j] = o; }
; }
; __global__ void __launch_bounds__(512, 2) fwd_mega(Args a) {
;     ...
;         for (int m = gw; m < BATCH * 256; m += NGW) rms_row_to_bf16(mem + (size_t)m * D, a.in[15], MEMN + (size_t)m * D, lane);
.LBB0_68:
	global_load_dwordx4 v[14:17], v[4:5], off offset:-2048
	global_load_dwordx4 v[18:21], v[4:5], off offset:-1024
	global_load_dwordx4 v[22:25], v[4:5], off
	global_load_dwordx4 v[26:29], v[4:5], off offset:1024
	global_load_dwordx4 v[30:33], v[0:1], off
	s_add_i32 s8, s8, s80
	v_lshl_add_u64 v[4:5], v[4:5], 0, s[6:7]
	s_cmpk_gt_i32 s8, 0x1ff
	s_waitcnt vmcnt(4)
	v_pk_mul_f32 v[34:35], v[16:17], v[16:17]
	v_pk_mul_f32 v[36:37], v[14:15], v[14:15]
	s_waitcnt vmcnt(3)
	v_pk_mul_f32 v[38:39], v[20:21], v[20:21]
	v_pk_mul_f32 v[40:41], v[18:19], v[18:19]
	v_pk_mov_b32 v[46:47], v[36:37], v[34:35] op_sel:[1,0]
	v_mov_b32_e32 v37, v35
	v_pk_mov_b32 v[34:35], v[40:41], v[38:39] op_sel:[1,0]
	v_mov_b32_e32 v41, v39
	s_waitcnt vmcnt(1)
	v_mul_f32_e32 v45, v27, v27
	v_mul_f32_e32 v42, v23, v23
	v_mul_f32_e32 v44, v25, v25
	v_pk_add_f32 v[36:37], v[46:47], v[36:37]
	v_pk_add_f32 v[34:35], v[34:35], v[40:41]
	v_mul_f32_e32 v13, v26, v26
	v_mul_f32_e32 v48, v28, v28
	v_mul_f32_e32 v49, v29, v29
	v_pk_fma_f32 v[38:39], v[22:23], v[22:23], v[42:43] op_sel_hi:[1,1,0]
	v_pk_fma_f32 v[42:43], v[24:25], v[24:25], v[44:45] op_sel_hi:[1,1,0]
	v_pk_add_f32 v[36:37], v[36:37], v[36:37] op_sel:[0,1] op_sel_hi:[1,0]
	v_pk_add_f32 v[34:35], v[34:35], v[34:35] op_sel:[0,1] op_sel_hi:[1,0]
	v_mov_b32_e32 v39, v48
	v_mov_b32_e32 v43, v49
	v_mov_b32_e32 v37, v13
	v_mov_b32_e32 v35, v45
	v_pk_add_f32 v[38:39], v[38:39], v[42:43]
	v_pk_add_f32 v[34:35], v[36:37], v[34:35]
	s_nop 0
	v_pk_add_f32 v[34:35], v[34:35], v[38:39]
	s_nop 0
	v_add_f32_e32 v13, v34, v35
	ds_bpermute_b32 v34, v6, v13
	s_waitcnt lgkmcnt(0)
	v_add_f32_e32 v13, v13, v34
	ds_bpermute_b32 v34, v7, v13
	s_waitcnt lgkmcnt(0)
	v_add_f32_e32 v13, v13, v34
	ds_bpermute_b32 v34, v8, v13
	s_waitcnt lgkmcnt(0)
	v_add_f32_e32 v13, v13, v34
	ds_bpermute_b32 v34, v9, v13
	s_waitcnt lgkmcnt(0)
	v_add_f32_e32 v13, v13, v34
	ds_bpermute_b32 v34, v10, v13
	s_waitcnt lgkmcnt(0)
	v_add_f32_e32 v13, v13, v34
	ds_bpermute_b32 v34, v11, v13
	s_waitcnt lgkmcnt(0)
	v_add_f32_e32 v13, v13, v34
	v_fmamk_f32 v13, v13, 0x3a800000, v12
	v_mul_f32_e32 v34, 0x4b800000, v13
	v_cmp_gt_f32_e32 vcc, s3, v13
	s_nop 1
	v_cndmask_b32_e32 v13, v13, v34, vcc
	v_rsq_f32_e32 v13, v13
	s_nop 0
	v_mul_f32_e32 v34, 0x45800000, v13
	v_cndmask_b32_e32 v34, v13, v34, vcc
	v_pk_mul_f32 v[14:15], v[14:15], v[34:35] op_sel_hi:[1,0]
	v_pk_mul_f32 v[16:17], v[16:17], v[34:35] op_sel_hi:[1,0]
	s_waitcnt vmcnt(0)
	v_pk_mul_f32 v[14:15], v[30:31], v[14:15]
	v_pk_mul_f32 v[16:17], v[32:33], v[16:17]
	v_cvt_pk_bf16_f32 v14, v14, v15
	v_cvt_pk_bf16_f32 v15, v16, v17
	global_store_dwordx2 v[2:3], v[14:15], off offset:-1536 sc1
	global_load_dwordx4 v[14:17], v[0:1], off offset:1024
	v_pk_mul_f32 v[18:19], v[18:19], v[34:35] op_sel_hi:[1,0]
	v_pk_mul_f32 v[20:21], v[20:21], v[34:35] op_sel_hi:[1,0]
	s_waitcnt vmcnt(0)
	v_pk_mul_f32 v[14:15], v[14:15], v[18:19]
	v_pk_mul_f32 v[16:17], v[16:17], v[20:21]
	v_cvt_pk_bf16_f32 v14, v14, v15
	v_cvt_pk_bf16_f32 v15, v16, v17
	global_store_dwordx2 v[2:3], v[14:15], off offset:-1024 sc1
	global_load_dwordx4 v[14:17], v[0:1], off offset:2048
	v_pk_mul_f32 v[18:19], v[22:23], v[34:35] op_sel_hi:[1,0]
	v_pk_mul_f32 v[20:21], v[24:25], v[34:35] op_sel_hi:[1,0]
	s_waitcnt vmcnt(0)
	v_pk_mul_f32 v[14:15], v[14:15], v[18:19]
	v_pk_mul_f32 v[16:17], v[16:17], v[20:21]
	v_cvt_pk_bf16_f32 v14, v14, v15
	v_cvt_pk_bf16_f32 v15, v16, v17
	global_store_dwordx2 v[2:3], v[14:15], off offset:-512 sc1
	global_load_dwordx4 v[14:17], v[0:1], off offset:3072
	v_pk_mul_f32 v[18:19], v[26:27], v[34:35] op_sel_hi:[1,0]
	v_pk_mul_f32 v[20:21], v[28:29], v[34:35] op_sel_hi:[1,0]
	s_waitcnt vmcnt(0)
	v_pk_mul_f32 v[14:15], v[14:15], v[18:19]
	v_pk_mul_f32 v[16:17], v[16:17], v[20:21]
	v_cvt_pk_bf16_f32 v14, v14, v15
	v_cvt_pk_bf16_f32 v15, v16, v17
	global_store_dwordx2 v[2:3], v[14:15], off sc1
	v_lshl_add_u64 v[2:3], v[2:3], 0, s[0:1]
	s_cbranch_scc0 .LBB0_68

; __device__ __forceinline__ unsigned xb_ld(unsigned* p)              { return __hip_atomic_load(p, __ATOMIC_RELAXED, __HIP_MEMORY_SCOPE_AGENT); }
; __device__ __forceinline__ unsigned xb_add(unsigned* p, unsigned v) { return __hip_atomic_fetch_add(p, v, __ATOMIC_RELAXED, __HIP_MEMORY_SCOPE_AGENT); }
; #define XB_SPIN(cond, bar) do { unsigned _sp = 0; while (cond) { __builtin_amdgcn_s_sleep(1); \
;     if ((++_sp & 255u) == 0u) { if (xb_ld(&(bar)[XB_TMO])) break; if (_sp > XB_SPIN_CAP) { atomicAdd(&(bar)[XB_TMO], 1u); break; } } } } while (0)
; __device__ __forceinline__ void xcd_barrier(const XcdBarrier& b) {
;     ...
;         const unsigned old = xb_add(&bar[XB_XSUB(b.x)], 1u);
;         const unsigned gen = old / nloc;
;         if (old + 1u == (gen + 1u) * nloc) {
;             __builtin_amdgcn_fence(__ATOMIC_RELEASE, "agent");
;             asm volatile("s_waitcnt vmcnt(0)" ::: "memory");
;             const unsigned og = xb_add(&bar[XB_TOP], 1u);
;             const unsigned tg = og / nx;
;             if (og + 1u == (tg + 1u) * nx) xb_add(&bar[XB_TOPGEN], 1u);
;             else XB_SPIN(xb_ld(&bar[XB_TOPGEN]) == tg, bar);
;             __builtin_amdgcn_fence(__ATOMIC_ACQUIRE, "agent");
;             xb_add(&bar[XB_XGEN(b.x)], 1u);
.LBB0_103:
	s_andn2_saveexec_b64 s[8:9], s[8:9]
	s_cbranch_execz .LBB0_123
	s_mov_b64 s[8:9], exec
	s_waitcnt lgkmcnt(0)
	s_waitcnt vmcnt(0)
	v_mbcnt_lo_u32_b32 v1, s8, 0
	v_mbcnt_hi_u32_b32 v1, s9, v1
	v_cmp_eq_u32_e32 vcc, 0, v1
	s_and_saveexec_b64 s[10:11], vcc
	s_cbranch_execz .LBB0_106
	s_bcnt1_i32_b64 s3, s[8:9]
	v_mov_b32_e32 v2, 0x4000
	v_mov_b32_e32 v3, s3
	global_atomic_add v2, v2, v3, s[84:85] offset:1024 sc0

; __device__ __forceinline__ unsigned xb_ld(unsigned* p)              { return __hip_atomic_load(p, __ATOMIC_RELAXED, __HIP_MEMORY_SCOPE_AGENT); }
; __device__ __forceinline__ unsigned xb_add(unsigned* p, unsigned v) { return __hip_atomic_fetch_add(p, v, __ATOMIC_RELAXED, __HIP_MEMORY_SCOPE_AGENT); }
; #define XB_SPIN(cond, bar) do { unsigned _sp = 0; while (cond) { __builtin_amdgcn_s_sleep(1); \
;     if ((++_sp & 255u) == 0u) { if (xb_ld(&(bar)[XB_TMO])) break; if (_sp > XB_SPIN_CAP) { atomicAdd(&(bar)[XB_TMO], 1u); break; } } } } while (0)
; __device__ __forceinline__ void xcd_barrier(const XcdBarrier& b) {
;     ...
;         const unsigned old = xb_add(&bar[XB_XSUB(b.x)], 1u);
;         const unsigned gen = old / nloc;
;         if (old + 1u == (gen + 1u) * nloc) {
;             __builtin_amdgcn_fence(__ATOMIC_RELEASE, "agent");
;             asm volatile("s_waitcnt vmcnt(0)" ::: "memory");
;             const unsigned og = xb_add(&bar[XB_TOP], 1u);
;             const unsigned tg = og / nx;
;             if (og + 1u == (tg + 1u) * nx) xb_add(&bar[XB_TOPGEN], 1u);
;             else XB_SPIN(xb_ld(&bar[XB_TOPGEN]) == tg, bar);
;             __builtin_amdgcn_fence(__ATOMIC_ACQUIRE, "agent");
;             xb_add(&bar[XB_XGEN(b.x)], 1u);
.LBB0_192:
	s_andn2_saveexec_b64 s[10:11], s[10:11]
	s_cbranch_execz .LBB0_212
	s_mov_b64 s[10:11], exec
	s_waitcnt lgkmcnt(0)
	s_waitcnt vmcnt(0)
	v_mbcnt_lo_u32_b32 v1, s10, 0
	v_mbcnt_hi_u32_b32 v1, s11, v1
	v_cmp_eq_u32_e32 vcc, 0, v1
	s_and_saveexec_b64 s[14:15], vcc
	s_cbranch_execz .LBB0_195
	s_bcnt1_i32_b64 s3, s[10:11]
	v_mov_b32_e32 v2, 0x4000
	v_mov_b32_e32 v3, s3
	global_atomic_add v2, v2, v3, s[84:85] offset:1024 sc0
